# v70 + de-serialized SGU-item epilogue in MLOC (bias and all 16 u loads first, counted waits)
# speedup vs baseline: 1.0160x; 1.0099x over previous
.LBB1_871:
	v_add_u32_e32 v3, s5, v60
	v_ashrrev_i32_e32 v8, 5, v3
	v_lshlrev_b32_e32 v4, 7, v8
	v_ashrrev_i32_e32 v5, 31, v4
	v_lshl_add_u64 v[4:5], v[4:5], 2, v[0:1]
	global_load_dwordx4 v[4:7], v[4:5], off
	s_addk_i32 s5, 0x400
	s_cmpk_lg_i32 s5, 0x1000
	s_waitcnt vmcnt(0)
	v_cvt_pk_bf16_f32 v4, v4, v5
	v_cvt_pk_bf16_f32 v5, v6, v7
	v_mad_u64_u32 v[6:7], s[6:7], v8, s3, v[2:3]
	ds_write_b64 v6, v[4:5] offset:34816
	v_add_u32_e32 v4, 0x100, v3
	v_ashrrev_i32_e32 v8, 5, v4
	v_lshlrev_b32_e32 v4, 7, v8
	v_ashrrev_i32_e32 v5, 31, v4
	v_lshl_add_u64 v[4:5], v[4:5], 2, v[0:1]
	global_load_dwordx4 v[4:7], v[4:5], off
	s_waitcnt vmcnt(0)
	v_cvt_pk_bf16_f32 v4, v4, v5
	v_cvt_pk_bf16_f32 v5, v6, v7
	v_mad_u64_u32 v[6:7], s[6:7], v8, s3, v[2:3]
	ds_write_b64 v6, v[4:5] offset:34816
	v_add_u32_e32 v4, 0x200, v3
	v_ashrrev_i32_e32 v8, 5, v4
	v_lshlrev_b32_e32 v4, 7, v8
	v_ashrrev_i32_e32 v5, 31, v4
	v_lshl_add_u64 v[4:5], v[4:5], 2, v[0:1]
	global_load_dwordx4 v[4:7], v[4:5], off
	s_waitcnt vmcnt(0)
	v_cvt_pk_bf16_f32 v4, v4, v5
	v_cvt_pk_bf16_f32 v5, v6, v7
	v_mad_u64_u32 v[6:7], s[6:7], v8, s3, v[2:3]
	v_add_u32_e32 v3, 0x300, v3
	v_ashrrev_i32_e32 v3, 5, v3
	ds_write_b64 v6, v[4:5] offset:34816
	v_lshlrev_b32_e32 v4, 7, v3
	v_ashrrev_i32_e32 v5, 31, v4
	v_lshl_add_u64 v[4:5], v[4:5], 2, v[0:1]
	global_load_dwordx4 v[4:7], v[4:5], off
	s_waitcnt vmcnt(0)
	v_cvt_pk_bf16_f32 v4, v4, v5
	v_cvt_pk_bf16_f32 v5, v6, v7
	v_mad_u64_u32 v[6:7], s[6:7], v3, s3, v[2:3]
	ds_write_b64 v6, v[4:5] offset:34816
	s_cbranch_scc1 .LBB1_871
	v_and_b32_e32 v25, 15, v60
	v_and_b32_e32 v0, 48, v60
	v_or_b32_e32 v126, v30, v25
	v_add_u32_e32 v24, 16, v0
	v_mad_u64_u32 v[26:27], s[6:7], v126, s3, v[24:25]
	v_mad_u32_u24 v61, v25, s3, v24
	s_waitcnt lgkmcnt(0)
	s_barrier
	ds_read_b128 v[0:3], v26 offset:34816
	ds_read_b128 v[4:7], v26 offset:34880
	ds_read_b128 v[8:11], v26 offset:34944
	ds_read_b128 v[32:35], v26 offset:35008
	ds_read_b128 v[12:15], v26 offset:39168
	ds_read_b128 v[16:19], v26 offset:39232
	ds_read_b128 v[20:23], v26 offset:39296
	ds_read_b128 v[62:65], v26 offset:39360
	ds_read_b128 v[24:27], v61
	ds_read_b128 v[28:31], v61 offset:4352
	ds_read_b128 v[36:39], v61 offset:8704
	ds_read_b128 v[40:43], v61 offset:13056
	ds_read_b128 v[44:47], v61 offset:17408
	ds_read_b128 v[48:51], v61 offset:21760
	ds_read_b128 v[52:55], v61 offset:26112
	ds_read_b128 v[56:59], v61 offset:30464
	s_setprio 1
	s_waitcnt lgkmcnt(7)
	v_mfma_f32_16x16x32_bf16 v[66:69], v[24:27], v[0:3], 0
	v_mfma_f32_16x16x32_bf16 v[24:27], v[24:27], v[12:15], 0
	s_waitcnt lgkmcnt(6)
	v_mfma_f32_16x16x32_bf16 v[70:73], v[28:31], v[0:3], 0
	v_mfma_f32_16x16x32_bf16 v[28:31], v[28:31], v[12:15], 0
	s_waitcnt lgkmcnt(5)
	v_mfma_f32_16x16x32_bf16 v[74:77], v[36:39], v[0:3], 0
	v_mfma_f32_16x16x32_bf16 v[36:39], v[36:39], v[12:15], 0
	s_waitcnt lgkmcnt(4)
	v_mfma_f32_16x16x32_bf16 v[78:81], v[40:43], v[0:3], 0
	v_mfma_f32_16x16x32_bf16 v[40:43], v[40:43], v[12:15], 0
	s_waitcnt lgkmcnt(3)
	v_mfma_f32_16x16x32_bf16 v[82:85], v[44:47], v[0:3], 0
	v_mfma_f32_16x16x32_bf16 v[44:47], v[44:47], v[12:15], 0
	s_waitcnt lgkmcnt(2)
	v_mfma_f32_16x16x32_bf16 v[86:89], v[48:51], v[0:3], 0
	v_mfma_f32_16x16x32_bf16 v[48:51], v[48:51], v[12:15], 0
	s_waitcnt lgkmcnt(1)
	v_mfma_f32_16x16x32_bf16 v[90:93], v[52:55], v[0:3], 0
	v_mfma_f32_16x16x32_bf16 v[52:55], v[52:55], v[12:15], 0
	s_waitcnt lgkmcnt(0)
	v_mfma_f32_16x16x32_bf16 v[0:3], v[56:59], v[0:3], 0
	v_mfma_f32_16x16x32_bf16 v[12:15], v[56:59], v[12:15], 0
	s_setprio 0
	ds_read_b128 v[56:59], v61 offset:64
	ds_read_b128 v[94:97], v61 offset:4416
	ds_read_b128 v[98:101], v61 offset:8768
	ds_read_b128 v[102:105], v61 offset:13120
	ds_read_b128 v[106:109], v61 offset:17472
	ds_read_b128 v[110:113], v61 offset:21824
	ds_read_b128 v[114:117], v61 offset:26176
	ds_read_b128 v[118:121], v61 offset:30528
	s_setprio 1
	s_waitcnt lgkmcnt(7)
	v_mfma_f32_16x16x32_bf16 v[66:69], v[56:59], v[4:7], v[66:69]
	v_mfma_f32_16x16x32_bf16 v[24:27], v[56:59], v[16:19], v[24:27]
	s_waitcnt lgkmcnt(6)
	v_mfma_f32_16x16x32_bf16 v[56:59], v[94:97], v[4:7], v[70:73]
	v_mfma_f32_16x16x32_bf16 v[28:31], v[94:97], v[16:19], v[28:31]
	s_waitcnt lgkmcnt(5)
	v_mfma_f32_16x16x32_bf16 v[70:73], v[98:101], v[4:7], v[74:77]
	v_mfma_f32_16x16x32_bf16 v[36:39], v[98:101], v[16:19], v[36:39]
	s_waitcnt lgkmcnt(4)
	v_mfma_f32_16x16x32_bf16 v[74:77], v[102:105], v[4:7], v[78:81]
	v_mfma_f32_16x16x32_bf16 v[40:43], v[102:105], v[16:19], v[40:43]
	s_waitcnt lgkmcnt(3)
	v_mfma_f32_16x16x32_bf16 v[78:81], v[106:109], v[4:7], v[82:85]
	v_mfma_f32_16x16x32_bf16 v[44:47], v[106:109], v[16:19], v[44:47]
	s_waitcnt lgkmcnt(2)
	v_mfma_f32_16x16x32_bf16 v[82:85], v[110:113], v[4:7], v[86:89]
	v_mfma_f32_16x16x32_bf16 v[48:51], v[110:113], v[16:19], v[48:51]
	s_waitcnt lgkmcnt(1)
	v_mfma_f32_16x16x32_bf16 v[86:89], v[114:117], v[4:7], v[90:93]
	v_mfma_f32_16x16x32_bf16 v[52:55], v[114:117], v[16:19], v[52:55]
	s_waitcnt lgkmcnt(0)
	v_mfma_f32_16x16x32_bf16 v[0:3], v[118:121], v[4:7], v[0:3]
	v_mfma_f32_16x16x32_bf16 v[4:7], v[118:121], v[16:19], v[12:15]
	s_setprio 0
	s_nop 1
	ds_read_b128 v[12:15], v61 offset:128
	ds_read_b128 v[16:19], v61 offset:4480
	ds_read_b128 v[90:93], v61 offset:8832
	ds_read_b128 v[94:97], v61 offset:13184
	ds_read_b128 v[98:101], v61 offset:17536
	ds_read_b128 v[102:105], v61 offset:21888
	ds_read_b128 v[106:109], v61 offset:26240
	ds_read_b128 v[110:113], v61 offset:30592
	s_setprio 1
	s_waitcnt lgkmcnt(7)
	v_mfma_f32_16x16x32_bf16 v[66:69], v[12:15], v[8:11], v[66:69]
	v_mfma_f32_16x16x32_bf16 v[12:15], v[12:15], v[20:23], v[24:27]
	s_waitcnt lgkmcnt(6)
	v_mfma_f32_16x16x32_bf16 v[24:27], v[16:19], v[8:11], v[56:59]
	v_mfma_f32_16x16x32_bf16 v[16:19], v[16:19], v[20:23], v[28:31]
	s_waitcnt lgkmcnt(5)
	v_mfma_f32_16x16x32_bf16 v[70:73], v[90:93], v[8:11], v[70:73]
	v_mfma_f32_16x16x32_bf16 v[36:39], v[90:93], v[20:23], v[36:39]
	s_waitcnt lgkmcnt(4)
	v_mfma_f32_16x16x32_bf16 v[74:77], v[94:97], v[8:11], v[74:77]
	v_mfma_f32_16x16x32_bf16 v[40:43], v[94:97], v[20:23], v[40:43]
	s_waitcnt lgkmcnt(3)
	v_mfma_f32_16x16x32_bf16 v[78:81], v[98:101], v[8:11], v[78:81]
	v_mfma_f32_16x16x32_bf16 v[90:93], v[98:101], v[20:23], v[44:47]
	s_waitcnt lgkmcnt(2)
	v_mfma_f32_16x16x32_bf16 v[82:85], v[102:105], v[8:11], v[82:85]
	v_mfma_f32_16x16x32_bf16 v[94:97], v[102:105], v[20:23], v[48:51]
	s_waitcnt lgkmcnt(1)
	v_mfma_f32_16x16x32_bf16 v[86:89], v[106:109], v[8:11], v[86:89]
	v_mfma_f32_16x16x32_bf16 v[98:101], v[106:109], v[20:23], v[52:55]
	s_waitcnt lgkmcnt(0)
	v_mfma_f32_16x16x32_bf16 v[0:3], v[110:113], v[8:11], v[0:3]
	v_mfma_f32_16x16x32_bf16 v[102:105], v[110:113], v[20:23], v[4:7]
	s_setprio 0
	s_nop 1
	ds_read_b128 v[4:7], v61 offset:192
	ds_read_b128 v[8:11], v61 offset:4544
	ds_read_b128 v[20:23], v61 offset:8896
	ds_read_b128 v[44:47], v61 offset:13248
	ds_read_b128 v[106:109], v61 offset:17600
	ds_read_b128 v[110:113], v61 offset:21952
	ds_read_b128 v[114:117], v61 offset:26304
	ds_read_b128 v[118:121], v61 offset:30656
	s_setprio 1
	s_waitcnt lgkmcnt(7)
	v_mfma_f32_16x16x32_bf16 v[122:125], v[4:7], v[32:35], v[66:69]
	v_mfma_f32_16x16x32_bf16 v[28:31], v[4:7], v[62:65], v[12:15]
	s_waitcnt lgkmcnt(6)
	v_mfma_f32_16x16x32_bf16 v[56:59], v[8:11], v[32:35], v[24:27]
	v_mfma_f32_16x16x32_bf16 v[24:27], v[8:11], v[62:65], v[16:19]
	s_waitcnt lgkmcnt(5)
	v_mfma_f32_16x16x32_bf16 v[52:55], v[20:23], v[32:35], v[70:73]
	v_mfma_f32_16x16x32_bf16 v[20:23], v[20:23], v[62:65], v[36:39]
	s_waitcnt lgkmcnt(4)
	v_mfma_f32_16x16x32_bf16 v[48:51], v[44:47], v[32:35], v[74:77]
	v_mfma_f32_16x16x32_bf16 v[16:19], v[44:47], v[62:65], v[40:43]
	s_waitcnt lgkmcnt(3)
	v_mfma_f32_16x16x32_bf16 v[44:47], v[106:109], v[32:35], v[78:81]
	v_mfma_f32_16x16x32_bf16 v[12:15], v[106:109], v[62:65], v[90:93]
	s_waitcnt lgkmcnt(2)
	v_mfma_f32_16x16x32_bf16 v[40:43], v[110:113], v[32:35], v[82:85]
	v_mfma_f32_16x16x32_bf16 v[8:11], v[110:113], v[62:65], v[94:97]
	s_waitcnt lgkmcnt(1)
	v_mfma_f32_16x16x32_bf16 v[36:39], v[114:117], v[32:35], v[86:89]
	v_mfma_f32_16x16x32_bf16 v[4:7], v[114:117], v[62:65], v[98:101]
	s_waitcnt lgkmcnt(0)
	v_mfma_f32_16x16x32_bf16 v[32:35], v[118:121], v[32:35], v[0:3]
	v_mfma_f32_16x16x32_bf16 v[0:3], v[118:121], v[62:65], v[102:105]
	s_setprio 0
	v_and_b32_e32 v118, 15, v168
	v_lshrrev_b32_e32 v119, 4, v168
	v_lshrrev_b32_e32 v120, 6, v162
	v_lshl_add_u32 v120, v120, 5, v118
	v_lshlrev_b32_e32 v114, 2, v120
	v_add_u32_e32 v120, s2, v120
	v_lshlrev_b32_e32 v119, 3, v119
	v_lshl_or_b32 v119, s4, 8, v119
	v_lshl_add_u32 v110, v120, 14, v119
	v_lshl_add_u32 v112, v120, 11, v119
	v_add_u32_e32 v120, 16, v120
	v_lshl_add_u32 v111, v120, 14, v119
	v_lshl_add_u32 v113, v120, 11, v119
	v_readlane_b32 s24, v241, 63
	v_readlane_b32 s25, v240, 0
	s_lshl_b64 s[42:43], s[96:97], 9
	s_nop 0
	s_add_u32 s24, s24, s42
	s_addc_u32 s25, s25, s43
	s_add_u32 s46, s76, 0x2000
	s_addc_u32 s47, s77, 0
	s_load_dwordx16 s[4:19], s[0:1], 0x140
	global_load_dword v116, v114, s[24:25]
	global_load_dword v117, v114, s[24:25] offset:64
	global_load_dwordx2 v[66:67], v110, s[46:47] offset:0
	global_load_dwordx2 v[68:69], v110, s[46:47] offset:32
	global_load_dwordx2 v[70:71], v110, s[46:47] offset:64
	global_load_dwordx2 v[72:73], v110, s[46:47] offset:96
	global_load_dwordx2 v[74:75], v110, s[46:47] offset:128
	global_load_dwordx2 v[76:77], v110, s[46:47] offset:160
	global_load_dwordx2 v[78:79], v110, s[46:47] offset:192
	global_load_dwordx2 v[80:81], v110, s[46:47] offset:224
	global_load_dwordx2 v[82:83], v111, s[46:47] offset:0
	global_load_dwordx2 v[84:85], v111, s[46:47] offset:32
	global_load_dwordx2 v[86:87], v111, s[46:47] offset:64
	global_load_dwordx2 v[88:89], v111, s[46:47] offset:96
	global_load_dwordx2 v[90:91], v111, s[46:47] offset:128
	global_load_dwordx2 v[92:93], v111, s[46:47] offset:160
	global_load_dwordx2 v[94:95], v111, s[46:47] offset:192
	global_load_dwordx2 v[96:97], v111, s[46:47] offset:224
	s_mov_b64 s[20:21], s[38:39]
	s_mov_b64 s[22:23], s[40:41]
	s_waitcnt lgkmcnt(0)
	s_waitcnt vmcnt(15)
	v_lshlrev_b32_e32 v98, 16, v66
	v_and_b32_e32 v99, 0xffff0000, v66
	v_lshlrev_b32_e32 v100, 16, v67
	v_and_b32_e32 v101, 0xffff0000, v67
	v_mul_f32_e32 v102, 0x3d372713, v98
	v_mul_f32_e32 v103, 0x3d372713, v99
	v_mul_f32_e32 v104, 0x3d372713, v100
	v_mul_f32_e32 v105, 0x3d372713, v101
	v_mul_f32_e32 v102, v102, v98
	v_mul_f32_e32 v103, v103, v99
	v_mul_f32_e32 v104, v104, v100
	v_mul_f32_e32 v105, v105, v101
	v_fma_f32 v102, v102, v98, v98
	v_fma_f32 v103, v103, v99, v99
	v_fma_f32 v104, v104, v100, v100
	v_fma_f32 v105, v105, v101, v101
	v_mul_f32_e32 v102, 0x3f4c422a, v102
	v_mul_f32_e32 v103, 0x3f4c422a, v103
	v_mul_f32_e32 v104, 0x3f4c422a, v104
	v_mul_f32_e32 v105, 0x3f4c422a, v105
	v_mul_f32_e32 v102, -2.0, v102
	v_mul_f32_e32 v103, -2.0, v103
	v_mul_f32_e32 v104, -2.0, v104
	v_mul_f32_e32 v105, -2.0, v105
	v_mul_f32_e32 v102, 0x3fb8aa3b, v102
	v_mul_f32_e32 v103, 0x3fb8aa3b, v103
	v_mul_f32_e32 v104, 0x3fb8aa3b, v104
	v_mul_f32_e32 v105, 0x3fb8aa3b, v105
	v_exp_f32_e32 v102, v102
	v_exp_f32_e32 v103, v103
	v_exp_f32_e32 v104, v104
	v_exp_f32_e32 v105, v105
	v_add_f32_e32 v102, 1.0, v102
	v_add_f32_e32 v103, 1.0, v103
	v_add_f32_e32 v104, 1.0, v104
	v_add_f32_e32 v105, 1.0, v105
	v_rcp_f32_e32 v102, v102
	v_rcp_f32_e32 v103, v103
	v_rcp_f32_e32 v104, v104
	v_rcp_f32_e32 v105, v105
	v_pk_add_f32 v[106:107], v[122:123], v[116:117] op_sel_hi:[1,0]
	v_pk_add_f32 v[108:109], v[124:125], v[116:117] op_sel_hi:[1,0]
	v_pk_mul_f32 v[98:99], v[102:103], v[98:99]
	v_pk_mul_f32 v[100:101], v[104:105], v[100:101]
	v_pk_mul_f32 v[98:99], v[106:107], v[98:99]
	v_pk_mul_f32 v[100:101], v[108:109], v[100:101]
	s_nop 0
	v_cvt_pk_bf16_f32 v106, v98, v99
	v_cvt_pk_bf16_f32 v107, v100, v101
	global_store_dwordx2 v112, v[106:107], s[12:13] offset:0
	s_waitcnt vmcnt(14)
	v_lshlrev_b32_e32 v98, 16, v68
	v_and_b32_e32 v99, 0xffff0000, v68
	v_lshlrev_b32_e32 v100, 16, v69
	v_and_b32_e32 v101, 0xffff0000, v69
	v_mul_f32_e32 v102, 0x3d372713, v98
	v_mul_f32_e32 v103, 0x3d372713, v99
	v_mul_f32_e32 v104, 0x3d372713, v100
	v_mul_f32_e32 v105, 0x3d372713, v101
	v_mul_f32_e32 v102, v102, v98
	v_mul_f32_e32 v103, v103, v99
	v_mul_f32_e32 v104, v104, v100
	v_mul_f32_e32 v105, v105, v101
	v_fma_f32 v102, v102, v98, v98
	v_fma_f32 v103, v103, v99, v99
	v_fma_f32 v104, v104, v100, v100
	v_fma_f32 v105, v105, v101, v101
	v_mul_f32_e32 v102, 0x3f4c422a, v102
	v_mul_f32_e32 v103, 0x3f4c422a, v103
	v_mul_f32_e32 v104, 0x3f4c422a, v104
	v_mul_f32_e32 v105, 0x3f4c422a, v105
	v_mul_f32_e32 v102, -2.0, v102
	v_mul_f32_e32 v103, -2.0, v103
	v_mul_f32_e32 v104, -2.0, v104
	v_mul_f32_e32 v105, -2.0, v105
	v_mul_f32_e32 v102, 0x3fb8aa3b, v102
	v_mul_f32_e32 v103, 0x3fb8aa3b, v103
	v_mul_f32_e32 v104, 0x3fb8aa3b, v104
	v_mul_f32_e32 v105, 0x3fb8aa3b, v105
	v_exp_f32_e32 v102, v102
	v_exp_f32_e32 v103, v103
	v_exp_f32_e32 v104, v104
	v_exp_f32_e32 v105, v105
	v_add_f32_e32 v102, 1.0, v102
	v_add_f32_e32 v103, 1.0, v103
	v_add_f32_e32 v104, 1.0, v104
	v_add_f32_e32 v105, 1.0, v105
	v_rcp_f32_e32 v102, v102
	v_rcp_f32_e32 v103, v103
	v_rcp_f32_e32 v104, v104
	v_rcp_f32_e32 v105, v105
	v_pk_add_f32 v[106:107], v[56:57], v[116:117] op_sel_hi:[1,0]
	v_pk_add_f32 v[108:109], v[58:59], v[116:117] op_sel_hi:[1,0]
	v_pk_mul_f32 v[98:99], v[102:103], v[98:99]
	v_pk_mul_f32 v[100:101], v[104:105], v[100:101]
	v_pk_mul_f32 v[98:99], v[106:107], v[98:99]
	v_pk_mul_f32 v[100:101], v[108:109], v[100:101]
	s_nop 0
	v_cvt_pk_bf16_f32 v106, v98, v99
	v_cvt_pk_bf16_f32 v107, v100, v101
	global_store_dwordx2 v112, v[106:107], s[12:13] offset:32
	s_waitcnt vmcnt(13)
	v_lshlrev_b32_e32 v98, 16, v70
	v_and_b32_e32 v99, 0xffff0000, v70
	v_lshlrev_b32_e32 v100, 16, v71
	v_and_b32_e32 v101, 0xffff0000, v71
	v_mul_f32_e32 v102, 0x3d372713, v98
	v_mul_f32_e32 v103, 0x3d372713, v99
	v_mul_f32_e32 v104, 0x3d372713, v100
	v_mul_f32_e32 v105, 0x3d372713, v101
	v_mul_f32_e32 v102, v102, v98
	v_mul_f32_e32 v103, v103, v99
	v_mul_f32_e32 v104, v104, v100
	v_mul_f32_e32 v105, v105, v101
	v_fma_f32 v102, v102, v98, v98
	v_fma_f32 v103, v103, v99, v99
	v_fma_f32 v104, v104, v100, v100
	v_fma_f32 v105, v105, v101, v101
	v_mul_f32_e32 v102, 0x3f4c422a, v102
	v_mul_f32_e32 v103, 0x3f4c422a, v103
	v_mul_f32_e32 v104, 0x3f4c422a, v104
	v_mul_f32_e32 v105, 0x3f4c422a, v105
	v_mul_f32_e32 v102, -2.0, v102
	v_mul_f32_e32 v103, -2.0, v103
	v_mul_f32_e32 v104, -2.0, v104
	v_mul_f32_e32 v105, -2.0, v105
	v_mul_f32_e32 v102, 0x3fb8aa3b, v102
	v_mul_f32_e32 v103, 0x3fb8aa3b, v103
	v_mul_f32_e32 v104, 0x3fb8aa3b, v104
	v_mul_f32_e32 v105, 0x3fb8aa3b, v105
	v_exp_f32_e32 v102, v102
	v_exp_f32_e32 v103, v103
	v_exp_f32_e32 v104, v104
	v_exp_f32_e32 v105, v105
	v_add_f32_e32 v102, 1.0, v102
	v_add_f32_e32 v103, 1.0, v103
	v_add_f32_e32 v104, 1.0, v104
	v_add_f32_e32 v105, 1.0, v105
	v_rcp_f32_e32 v102, v102
	v_rcp_f32_e32 v103, v103
	v_rcp_f32_e32 v104, v104
	v_rcp_f32_e32 v105, v105
	v_pk_add_f32 v[106:107], v[52:53], v[116:117] op_sel_hi:[1,0]
	v_pk_add_f32 v[108:109], v[54:55], v[116:117] op_sel_hi:[1,0]
	v_pk_mul_f32 v[98:99], v[102:103], v[98:99]
	v_pk_mul_f32 v[100:101], v[104:105], v[100:101]
	v_pk_mul_f32 v[98:99], v[106:107], v[98:99]
	v_pk_mul_f32 v[100:101], v[108:109], v[100:101]
	s_nop 0
	v_cvt_pk_bf16_f32 v106, v98, v99
	v_cvt_pk_bf16_f32 v107, v100, v101
	global_store_dwordx2 v112, v[106:107], s[12:13] offset:64
	s_waitcnt vmcnt(12)
	v_lshlrev_b32_e32 v98, 16, v72
	v_and_b32_e32 v99, 0xffff0000, v72
	v_lshlrev_b32_e32 v100, 16, v73
	v_and_b32_e32 v101, 0xffff0000, v73
	v_mul_f32_e32 v102, 0x3d372713, v98
	v_mul_f32_e32 v103, 0x3d372713, v99
	v_mul_f32_e32 v104, 0x3d372713, v100
	v_mul_f32_e32 v105, 0x3d372713, v101
	v_mul_f32_e32 v102, v102, v98
	v_mul_f32_e32 v103, v103, v99
	v_mul_f32_e32 v104, v104, v100
	v_mul_f32_e32 v105, v105, v101
	v_fma_f32 v102, v102, v98, v98
	v_fma_f32 v103, v103, v99, v99
	v_fma_f32 v104, v104, v100, v100
	v_fma_f32 v105, v105, v101, v101
	v_mul_f32_e32 v102, 0x3f4c422a, v102
	v_mul_f32_e32 v103, 0x3f4c422a, v103
	v_mul_f32_e32 v104, 0x3f4c422a, v104
	v_mul_f32_e32 v105, 0x3f4c422a, v105
	v_mul_f32_e32 v102, -2.0, v102
	v_mul_f32_e32 v103, -2.0, v103
	v_mul_f32_e32 v104, -2.0, v104
	v_mul_f32_e32 v105, -2.0, v105
	v_mul_f32_e32 v102, 0x3fb8aa3b, v102
	v_mul_f32_e32 v103, 0x3fb8aa3b, v103
	v_mul_f32_e32 v104, 0x3fb8aa3b, v104
	v_mul_f32_e32 v105, 0x3fb8aa3b, v105
	v_exp_f32_e32 v102, v102
	v_exp_f32_e32 v103, v103
	v_exp_f32_e32 v104, v104
	v_exp_f32_e32 v105, v105
	v_add_f32_e32 v102, 1.0, v102
	v_add_f32_e32 v103, 1.0, v103
	v_add_f32_e32 v104, 1.0, v104
	v_add_f32_e32 v105, 1.0, v105
	v_rcp_f32_e32 v102, v102
	v_rcp_f32_e32 v103, v103
	v_rcp_f32_e32 v104, v104
	v_rcp_f32_e32 v105, v105
	v_pk_add_f32 v[106:107], v[48:49], v[116:117] op_sel_hi:[1,0]
	v_pk_add_f32 v[108:109], v[50:51], v[116:117] op_sel_hi:[1,0]
	v_pk_mul_f32 v[98:99], v[102:103], v[98:99]
	v_pk_mul_f32 v[100:101], v[104:105], v[100:101]
	v_pk_mul_f32 v[98:99], v[106:107], v[98:99]
	v_pk_mul_f32 v[100:101], v[108:109], v[100:101]
	s_nop 0
	v_cvt_pk_bf16_f32 v106, v98, v99
	v_cvt_pk_bf16_f32 v107, v100, v101
	global_store_dwordx2 v112, v[106:107], s[12:13] offset:96
	s_waitcnt vmcnt(11)
	v_lshlrev_b32_e32 v98, 16, v74
	v_and_b32_e32 v99, 0xffff0000, v74
	v_lshlrev_b32_e32 v100, 16, v75
	v_and_b32_e32 v101, 0xffff0000, v75
	v_mul_f32_e32 v102, 0x3d372713, v98
	v_mul_f32_e32 v103, 0x3d372713, v99
	v_mul_f32_e32 v104, 0x3d372713, v100
	v_mul_f32_e32 v105, 0x3d372713, v101
	v_mul_f32_e32 v102, v102, v98
	v_mul_f32_e32 v103, v103, v99
	v_mul_f32_e32 v104, v104, v100
	v_mul_f32_e32 v105, v105, v101
	v_fma_f32 v102, v102, v98, v98
	v_fma_f32 v103, v103, v99, v99
	v_fma_f32 v104, v104, v100, v100
	v_fma_f32 v105, v105, v101, v101
	v_mul_f32_e32 v102, 0x3f4c422a, v102
	v_mul_f32_e32 v103, 0x3f4c422a, v103
	v_mul_f32_e32 v104, 0x3f4c422a, v104
	v_mul_f32_e32 v105, 0x3f4c422a, v105
	v_mul_f32_e32 v102, -2.0, v102
	v_mul_f32_e32 v103, -2.0, v103
	v_mul_f32_e32 v104, -2.0, v104
	v_mul_f32_e32 v105, -2.0, v105
	v_mul_f32_e32 v102, 0x3fb8aa3b, v102
	v_mul_f32_e32 v103, 0x3fb8aa3b, v103
	v_mul_f32_e32 v104, 0x3fb8aa3b, v104
	v_mul_f32_e32 v105, 0x3fb8aa3b, v105
	v_exp_f32_e32 v102, v102
	v_exp_f32_e32 v103, v103
	v_exp_f32_e32 v104, v104
	v_exp_f32_e32 v105, v105
	v_add_f32_e32 v102, 1.0, v102
	v_add_f32_e32 v103, 1.0, v103
	v_add_f32_e32 v104, 1.0, v104
	v_add_f32_e32 v105, 1.0, v105
	v_rcp_f32_e32 v102, v102
	v_rcp_f32_e32 v103, v103
	v_rcp_f32_e32 v104, v104
	v_rcp_f32_e32 v105, v105
	v_pk_add_f32 v[106:107], v[44:45], v[116:117] op_sel_hi:[1,0]
	v_pk_add_f32 v[108:109], v[46:47], v[116:117] op_sel_hi:[1,0]
	v_pk_mul_f32 v[98:99], v[102:103], v[98:99]
	v_pk_mul_f32 v[100:101], v[104:105], v[100:101]
	v_pk_mul_f32 v[98:99], v[106:107], v[98:99]
	v_pk_mul_f32 v[100:101], v[108:109], v[100:101]
	s_nop 0
	v_cvt_pk_bf16_f32 v106, v98, v99
	v_cvt_pk_bf16_f32 v107, v100, v101
	global_store_dwordx2 v112, v[106:107], s[12:13] offset:128
	s_waitcnt vmcnt(10)
	v_lshlrev_b32_e32 v98, 16, v76
	v_and_b32_e32 v99, 0xffff0000, v76
	v_lshlrev_b32_e32 v100, 16, v77
	v_and_b32_e32 v101, 0xffff0000, v77
	v_mul_f32_e32 v102, 0x3d372713, v98
	v_mul_f32_e32 v103, 0x3d372713, v99
	v_mul_f32_e32 v104, 0x3d372713, v100
	v_mul_f32_e32 v105, 0x3d372713, v101
	v_mul_f32_e32 v102, v102, v98
	v_mul_f32_e32 v103, v103, v99
	v_mul_f32_e32 v104, v104, v100
	v_mul_f32_e32 v105, v105, v101
	v_fma_f32 v102, v102, v98, v98
	v_fma_f32 v103, v103, v99, v99
	v_fma_f32 v104, v104, v100, v100
	v_fma_f32 v105, v105, v101, v101
	v_mul_f32_e32 v102, 0x3f4c422a, v102
	v_mul_f32_e32 v103, 0x3f4c422a, v103
	v_mul_f32_e32 v104, 0x3f4c422a, v104
	v_mul_f32_e32 v105, 0x3f4c422a, v105
	v_mul_f32_e32 v102, -2.0, v102
	v_mul_f32_e32 v103, -2.0, v103
	v_mul_f32_e32 v104, -2.0, v104
	v_mul_f32_e32 v105, -2.0, v105
	v_mul_f32_e32 v102, 0x3fb8aa3b, v102
	v_mul_f32_e32 v103, 0x3fb8aa3b, v103
	v_mul_f32_e32 v104, 0x3fb8aa3b, v104
	v_mul_f32_e32 v105, 0x3fb8aa3b, v105
	v_exp_f32_e32 v102, v102
	v_exp_f32_e32 v103, v103
	v_exp_f32_e32 v104, v104
	v_exp_f32_e32 v105, v105
	v_add_f32_e32 v102, 1.0, v102
	v_add_f32_e32 v103, 1.0, v103
	v_add_f32_e32 v104, 1.0, v104
	v_add_f32_e32 v105, 1.0, v105
	v_rcp_f32_e32 v102, v102
	v_rcp_f32_e32 v103, v103
	v_rcp_f32_e32 v104, v104
	v_rcp_f32_e32 v105, v105
	v_pk_add_f32 v[106:107], v[40:41], v[116:117] op_sel_hi:[1,0]
	v_pk_add_f32 v[108:109], v[42:43], v[116:117] op_sel_hi:[1,0]
	v_pk_mul_f32 v[98:99], v[102:103], v[98:99]
	v_pk_mul_f32 v[100:101], v[104:105], v[100:101]
	v_pk_mul_f32 v[98:99], v[106:107], v[98:99]
	v_pk_mul_f32 v[100:101], v[108:109], v[100:101]
	s_nop 0
	v_cvt_pk_bf16_f32 v106, v98, v99
	v_cvt_pk_bf16_f32 v107, v100, v101
	global_store_dwordx2 v112, v[106:107], s[12:13] offset:160
	s_waitcnt vmcnt(9)
	v_lshlrev_b32_e32 v98, 16, v78
	v_and_b32_e32 v99, 0xffff0000, v78
	v_lshlrev_b32_e32 v100, 16, v79
	v_and_b32_e32 v101, 0xffff0000, v79
	v_mul_f32_e32 v102, 0x3d372713, v98
	v_mul_f32_e32 v103, 0x3d372713, v99
	v_mul_f32_e32 v104, 0x3d372713, v100
	v_mul_f32_e32 v105, 0x3d372713, v101
	v_mul_f32_e32 v102, v102, v98
	v_mul_f32_e32 v103, v103, v99
	v_mul_f32_e32 v104, v104, v100
	v_mul_f32_e32 v105, v105, v101
	v_fma_f32 v102, v102, v98, v98
	v_fma_f32 v103, v103, v99, v99
	v_fma_f32 v104, v104, v100, v100
	v_fma_f32 v105, v105, v101, v101
	v_mul_f32_e32 v102, 0x3f4c422a, v102
	v_mul_f32_e32 v103, 0x3f4c422a, v103
	v_mul_f32_e32 v104, 0x3f4c422a, v104
	v_mul_f32_e32 v105, 0x3f4c422a, v105
	v_mul_f32_e32 v102, -2.0, v102
	v_mul_f32_e32 v103, -2.0, v103
	v_mul_f32_e32 v104, -2.0, v104
	v_mul_f32_e32 v105, -2.0, v105
	v_mul_f32_e32 v102, 0x3fb8aa3b, v102
	v_mul_f32_e32 v103, 0x3fb8aa3b, v103
	v_mul_f32_e32 v104, 0x3fb8aa3b, v104
	v_mul_f32_e32 v105, 0x3fb8aa3b, v105
	v_exp_f32_e32 v102, v102
	v_exp_f32_e32 v103, v103
	v_exp_f32_e32 v104, v104
	v_exp_f32_e32 v105, v105
	v_add_f32_e32 v102, 1.0, v102
	v_add_f32_e32 v103, 1.0, v103
	v_add_f32_e32 v104, 1.0, v104
	v_add_f32_e32 v105, 1.0, v105
	v_rcp_f32_e32 v102, v102
	v_rcp_f32_e32 v103, v103
	v_rcp_f32_e32 v104, v104
	v_rcp_f32_e32 v105, v105
	v_pk_add_f32 v[106:107], v[36:37], v[116:117] op_sel_hi:[1,0]
	v_pk_add_f32 v[108:109], v[38:39], v[116:117] op_sel_hi:[1,0]
	v_pk_mul_f32 v[98:99], v[102:103], v[98:99]
	v_pk_mul_f32 v[100:101], v[104:105], v[100:101]
	v_pk_mul_f32 v[98:99], v[106:107], v[98:99]
	v_pk_mul_f32 v[100:101], v[108:109], v[100:101]
	s_nop 0
	v_cvt_pk_bf16_f32 v106, v98, v99
	v_cvt_pk_bf16_f32 v107, v100, v101
	global_store_dwordx2 v112, v[106:107], s[12:13] offset:192
	s_waitcnt vmcnt(8)
	v_lshlrev_b32_e32 v98, 16, v80
	v_and_b32_e32 v99, 0xffff0000, v80
	v_lshlrev_b32_e32 v100, 16, v81
	v_and_b32_e32 v101, 0xffff0000, v81
	v_mul_f32_e32 v102, 0x3d372713, v98
	v_mul_f32_e32 v103, 0x3d372713, v99
	v_mul_f32_e32 v104, 0x3d372713, v100
	v_mul_f32_e32 v105, 0x3d372713, v101
	v_mul_f32_e32 v102, v102, v98
	v_mul_f32_e32 v103, v103, v99
	v_mul_f32_e32 v104, v104, v100
	v_mul_f32_e32 v105, v105, v101
	v_fma_f32 v102, v102, v98, v98
	v_fma_f32 v103, v103, v99, v99
	v_fma_f32 v104, v104, v100, v100
	v_fma_f32 v105, v105, v101, v101
	v_mul_f32_e32 v102, 0x3f4c422a, v102
	v_mul_f32_e32 v103, 0x3f4c422a, v103
	v_mul_f32_e32 v104, 0x3f4c422a, v104
	v_mul_f32_e32 v105, 0x3f4c422a, v105
	v_mul_f32_e32 v102, -2.0, v102
	v_mul_f32_e32 v103, -2.0, v103
	v_mul_f32_e32 v104, -2.0, v104
	v_mul_f32_e32 v105, -2.0, v105
	v_mul_f32_e32 v102, 0x3fb8aa3b, v102
	v_mul_f32_e32 v103, 0x3fb8aa3b, v103
	v_mul_f32_e32 v104, 0x3fb8aa3b, v104
	v_mul_f32_e32 v105, 0x3fb8aa3b, v105
	v_exp_f32_e32 v102, v102
	v_exp_f32_e32 v103, v103
	v_exp_f32_e32 v104, v104
	v_exp_f32_e32 v105, v105
	v_add_f32_e32 v102, 1.0, v102
	v_add_f32_e32 v103, 1.0, v103
	v_add_f32_e32 v104, 1.0, v104
	v_add_f32_e32 v105, 1.0, v105
	v_rcp_f32_e32 v102, v102
	v_rcp_f32_e32 v103, v103
	v_rcp_f32_e32 v104, v104
	v_rcp_f32_e32 v105, v105
	v_pk_add_f32 v[106:107], v[32:33], v[116:117] op_sel_hi:[1,0]
	v_pk_add_f32 v[108:109], v[34:35], v[116:117] op_sel_hi:[1,0]
	v_pk_mul_f32 v[98:99], v[102:103], v[98:99]
	v_pk_mul_f32 v[100:101], v[104:105], v[100:101]
	v_pk_mul_f32 v[98:99], v[106:107], v[98:99]
	v_pk_mul_f32 v[100:101], v[108:109], v[100:101]
	s_nop 0
	v_cvt_pk_bf16_f32 v106, v98, v99
	v_cvt_pk_bf16_f32 v107, v100, v101
	global_store_dwordx2 v112, v[106:107], s[12:13] offset:224
	s_waitcnt vmcnt(7)
	v_lshlrev_b32_e32 v98, 16, v82
	v_and_b32_e32 v99, 0xffff0000, v82
	v_lshlrev_b32_e32 v100, 16, v83
	v_and_b32_e32 v101, 0xffff0000, v83
	v_mul_f32_e32 v102, 0x3d372713, v98
	v_mul_f32_e32 v103, 0x3d372713, v99
	v_mul_f32_e32 v104, 0x3d372713, v100
	v_mul_f32_e32 v105, 0x3d372713, v101
	v_mul_f32_e32 v102, v102, v98
	v_mul_f32_e32 v103, v103, v99
	v_mul_f32_e32 v104, v104, v100
	v_mul_f32_e32 v105, v105, v101
	v_fma_f32 v102, v102, v98, v98
	v_fma_f32 v103, v103, v99, v99
	v_fma_f32 v104, v104, v100, v100
	v_fma_f32 v105, v105, v101, v101
	v_mul_f32_e32 v102, 0x3f4c422a, v102
	v_mul_f32_e32 v103, 0x3f4c422a, v103
	v_mul_f32_e32 v104, 0x3f4c422a, v104
	v_mul_f32_e32 v105, 0x3f4c422a, v105
	v_mul_f32_e32 v102, -2.0, v102
	v_mul_f32_e32 v103, -2.0, v103
	v_mul_f32_e32 v104, -2.0, v104
	v_mul_f32_e32 v105, -2.0, v105
	v_mul_f32_e32 v102, 0x3fb8aa3b, v102
	v_mul_f32_e32 v103, 0x3fb8aa3b, v103
	v_mul_f32_e32 v104, 0x3fb8aa3b, v104
	v_mul_f32_e32 v105, 0x3fb8aa3b, v105
	v_exp_f32_e32 v102, v102
	v_exp_f32_e32 v103, v103
	v_exp_f32_e32 v104, v104
	v_exp_f32_e32 v105, v105
	v_add_f32_e32 v102, 1.0, v102
	v_add_f32_e32 v103, 1.0, v103
	v_add_f32_e32 v104, 1.0, v104
	v_add_f32_e32 v105, 1.0, v105
	v_rcp_f32_e32 v102, v102
	v_rcp_f32_e32 v103, v103
	v_rcp_f32_e32 v104, v104
	v_rcp_f32_e32 v105, v105
	v_pk_add_f32 v[106:107], v[28:29], v[116:117] op_sel:[0,1] op_sel_hi:[1,1]
	v_pk_add_f32 v[108:109], v[30:31], v[116:117] op_sel:[0,1] op_sel_hi:[1,1]
	v_pk_mul_f32 v[98:99], v[102:103], v[98:99]
	v_pk_mul_f32 v[100:101], v[104:105], v[100:101]
	v_pk_mul_f32 v[98:99], v[106:107], v[98:99]
	v_pk_mul_f32 v[100:101], v[108:109], v[100:101]
	s_nop 0
	v_cvt_pk_bf16_f32 v106, v98, v99
	v_cvt_pk_bf16_f32 v107, v100, v101
	global_store_dwordx2 v113, v[106:107], s[12:13] offset:0
	s_waitcnt vmcnt(6)
	v_lshlrev_b32_e32 v98, 16, v84
	v_and_b32_e32 v99, 0xffff0000, v84
	v_lshlrev_b32_e32 v100, 16, v85
	v_and_b32_e32 v101, 0xffff0000, v85
	v_mul_f32_e32 v102, 0x3d372713, v98
	v_mul_f32_e32 v103, 0x3d372713, v99
	v_mul_f32_e32 v104, 0x3d372713, v100
	v_mul_f32_e32 v105, 0x3d372713, v101
	v_mul_f32_e32 v102, v102, v98
	v_mul_f32_e32 v103, v103, v99
	v_mul_f32_e32 v104, v104, v100
	v_mul_f32_e32 v105, v105, v101
	v_fma_f32 v102, v102, v98, v98
	v_fma_f32 v103, v103, v99, v99
	v_fma_f32 v104, v104, v100, v100
	v_fma_f32 v105, v105, v101, v101
	v_mul_f32_e32 v102, 0x3f4c422a, v102
	v_mul_f32_e32 v103, 0x3f4c422a, v103
	v_mul_f32_e32 v104, 0x3f4c422a, v104
	v_mul_f32_e32 v105, 0x3f4c422a, v105
	v_mul_f32_e32 v102, -2.0, v102
	v_mul_f32_e32 v103, -2.0, v103
	v_mul_f32_e32 v104, -2.0, v104
	v_mul_f32_e32 v105, -2.0, v105
	v_mul_f32_e32 v102, 0x3fb8aa3b, v102
	v_mul_f32_e32 v103, 0x3fb8aa3b, v103
	v_mul_f32_e32 v104, 0x3fb8aa3b, v104
	v_mul_f32_e32 v105, 0x3fb8aa3b, v105
	v_exp_f32_e32 v102, v102
	v_exp_f32_e32 v103, v103
	v_exp_f32_e32 v104, v104
	v_exp_f32_e32 v105, v105
	v_add_f32_e32 v102, 1.0, v102
	v_add_f32_e32 v103, 1.0, v103
	v_add_f32_e32 v104, 1.0, v104
	v_add_f32_e32 v105, 1.0, v105
	v_rcp_f32_e32 v102, v102
	v_rcp_f32_e32 v103, v103
	v_rcp_f32_e32 v104, v104
	v_rcp_f32_e32 v105, v105
	v_pk_add_f32 v[106:107], v[24:25], v[116:117] op_sel:[0,1] op_sel_hi:[1,1]
	v_pk_add_f32 v[108:109], v[26:27], v[116:117] op_sel:[0,1] op_sel_hi:[1,1]
	v_pk_mul_f32 v[98:99], v[102:103], v[98:99]
	v_pk_mul_f32 v[100:101], v[104:105], v[100:101]
	v_pk_mul_f32 v[98:99], v[106:107], v[98:99]
	v_pk_mul_f32 v[100:101], v[108:109], v[100:101]
	s_nop 0
	v_cvt_pk_bf16_f32 v106, v98, v99
	v_cvt_pk_bf16_f32 v107, v100, v101
	global_store_dwordx2 v113, v[106:107], s[12:13] offset:32
	s_waitcnt vmcnt(5)
	v_lshlrev_b32_e32 v98, 16, v86
	v_and_b32_e32 v99, 0xffff0000, v86
	v_lshlrev_b32_e32 v100, 16, v87
	v_and_b32_e32 v101, 0xffff0000, v87
	v_mul_f32_e32 v102, 0x3d372713, v98
	v_mul_f32_e32 v103, 0x3d372713, v99
	v_mul_f32_e32 v104, 0x3d372713, v100
	v_mul_f32_e32 v105, 0x3d372713, v101
	v_mul_f32_e32 v102, v102, v98
	v_mul_f32_e32 v103, v103, v99
	v_mul_f32_e32 v104, v104, v100
	v_mul_f32_e32 v105, v105, v101
	v_fma_f32 v102, v102, v98, v98
	v_fma_f32 v103, v103, v99, v99
	v_fma_f32 v104, v104, v100, v100
	v_fma_f32 v105, v105, v101, v101
	v_mul_f32_e32 v102, 0x3f4c422a, v102
	v_mul_f32_e32 v103, 0x3f4c422a, v103
	v_mul_f32_e32 v104, 0x3f4c422a, v104
	v_mul_f32_e32 v105, 0x3f4c422a, v105
	v_mul_f32_e32 v102, -2.0, v102
	v_mul_f32_e32 v103, -2.0, v103
	v_mul_f32_e32 v104, -2.0, v104
	v_mul_f32_e32 v105, -2.0, v105
	v_mul_f32_e32 v102, 0x3fb8aa3b, v102
	v_mul_f32_e32 v103, 0x3fb8aa3b, v103
	v_mul_f32_e32 v104, 0x3fb8aa3b, v104
	v_mul_f32_e32 v105, 0x3fb8aa3b, v105
	v_exp_f32_e32 v102, v102
	v_exp_f32_e32 v103, v103
	v_exp_f32_e32 v104, v104
	v_exp_f32_e32 v105, v105
	v_add_f32_e32 v102, 1.0, v102
	v_add_f32_e32 v103, 1.0, v103
	v_add_f32_e32 v104, 1.0, v104
	v_add_f32_e32 v105, 1.0, v105
	v_rcp_f32_e32 v102, v102
	v_rcp_f32_e32 v103, v103
	v_rcp_f32_e32 v104, v104
	v_rcp_f32_e32 v105, v105
	v_pk_add_f32 v[106:107], v[20:21], v[116:117] op_sel:[0,1] op_sel_hi:[1,1]
	v_pk_add_f32 v[108:109], v[22:23], v[116:117] op_sel:[0,1] op_sel_hi:[1,1]
	v_pk_mul_f32 v[98:99], v[102:103], v[98:99]
	v_pk_mul_f32 v[100:101], v[104:105], v[100:101]
	v_pk_mul_f32 v[98:99], v[106:107], v[98:99]
	v_pk_mul_f32 v[100:101], v[108:109], v[100:101]
	s_nop 0
	v_cvt_pk_bf16_f32 v106, v98, v99
	v_cvt_pk_bf16_f32 v107, v100, v101
	global_store_dwordx2 v113, v[106:107], s[12:13] offset:64
	s_waitcnt vmcnt(4)
	v_lshlrev_b32_e32 v98, 16, v88
	v_and_b32_e32 v99, 0xffff0000, v88
	v_lshlrev_b32_e32 v100, 16, v89
	v_and_b32_e32 v101, 0xffff0000, v89
	v_mul_f32_e32 v102, 0x3d372713, v98
	v_mul_f32_e32 v103, 0x3d372713, v99
	v_mul_f32_e32 v104, 0x3d372713, v100
	v_mul_f32_e32 v105, 0x3d372713, v101
	v_mul_f32_e32 v102, v102, v98
	v_mul_f32_e32 v103, v103, v99
	v_mul_f32_e32 v104, v104, v100
	v_mul_f32_e32 v105, v105, v101
	v_fma_f32 v102, v102, v98, v98
	v_fma_f32 v103, v103, v99, v99
	v_fma_f32 v104, v104, v100, v100
	v_fma_f32 v105, v105, v101, v101
	v_mul_f32_e32 v102, 0x3f4c422a, v102
	v_mul_f32_e32 v103, 0x3f4c422a, v103
	v_mul_f32_e32 v104, 0x3f4c422a, v104
	v_mul_f32_e32 v105, 0x3f4c422a, v105
	v_mul_f32_e32 v102, -2.0, v102
	v_mul_f32_e32 v103, -2.0, v103
	v_mul_f32_e32 v104, -2.0, v104
	v_mul_f32_e32 v105, -2.0, v105
	v_mul_f32_e32 v102, 0x3fb8aa3b, v102
	v_mul_f32_e32 v103, 0x3fb8aa3b, v103
	v_mul_f32_e32 v104, 0x3fb8aa3b, v104
	v_mul_f32_e32 v105, 0x3fb8aa3b, v105
	v_exp_f32_e32 v102, v102
	v_exp_f32_e32 v103, v103
	v_exp_f32_e32 v104, v104
	v_exp_f32_e32 v105, v105
	v_add_f32_e32 v102, 1.0, v102
	v_add_f32_e32 v103, 1.0, v103
	v_add_f32_e32 v104, 1.0, v104
	v_add_f32_e32 v105, 1.0, v105
	v_rcp_f32_e32 v102, v102
	v_rcp_f32_e32 v103, v103
	v_rcp_f32_e32 v104, v104
	v_rcp_f32_e32 v105, v105
	v_pk_add_f32 v[106:107], v[16:17], v[116:117] op_sel:[0,1] op_sel_hi:[1,1]
	v_pk_add_f32 v[108:109], v[18:19], v[116:117] op_sel:[0,1] op_sel_hi:[1,1]
	v_pk_mul_f32 v[98:99], v[102:103], v[98:99]
	v_pk_mul_f32 v[100:101], v[104:105], v[100:101]
	v_pk_mul_f32 v[98:99], v[106:107], v[98:99]
	v_pk_mul_f32 v[100:101], v[108:109], v[100:101]
	s_nop 0
	v_cvt_pk_bf16_f32 v106, v98, v99
	v_cvt_pk_bf16_f32 v107, v100, v101
	global_store_dwordx2 v113, v[106:107], s[12:13] offset:96
	s_waitcnt vmcnt(3)
	v_lshlrev_b32_e32 v98, 16, v90
	v_and_b32_e32 v99, 0xffff0000, v90
	v_lshlrev_b32_e32 v100, 16, v91
	v_and_b32_e32 v101, 0xffff0000, v91
	v_mul_f32_e32 v102, 0x3d372713, v98
	v_mul_f32_e32 v103, 0x3d372713, v99
	v_mul_f32_e32 v104, 0x3d372713, v100
	v_mul_f32_e32 v105, 0x3d372713, v101
	v_mul_f32_e32 v102, v102, v98
	v_mul_f32_e32 v103, v103, v99
	v_mul_f32_e32 v104, v104, v100
	v_mul_f32_e32 v105, v105, v101
	v_fma_f32 v102, v102, v98, v98
	v_fma_f32 v103, v103, v99, v99
	v_fma_f32 v104, v104, v100, v100
	v_fma_f32 v105, v105, v101, v101
	v_mul_f32_e32 v102, 0x3f4c422a, v102
	v_mul_f32_e32 v103, 0x3f4c422a, v103
	v_mul_f32_e32 v104, 0x3f4c422a, v104
	v_mul_f32_e32 v105, 0x3f4c422a, v105
	v_mul_f32_e32 v102, -2.0, v102
	v_mul_f32_e32 v103, -2.0, v103
	v_mul_f32_e32 v104, -2.0, v104
	v_mul_f32_e32 v105, -2.0, v105
	v_mul_f32_e32 v102, 0x3fb8aa3b, v102
	v_mul_f32_e32 v103, 0x3fb8aa3b, v103
	v_mul_f32_e32 v104, 0x3fb8aa3b, v104
	v_mul_f32_e32 v105, 0x3fb8aa3b, v105
	v_exp_f32_e32 v102, v102
	v_exp_f32_e32 v103, v103
	v_exp_f32_e32 v104, v104
	v_exp_f32_e32 v105, v105
	v_add_f32_e32 v102, 1.0, v102
	v_add_f32_e32 v103, 1.0, v103
	v_add_f32_e32 v104, 1.0, v104
	v_add_f32_e32 v105, 1.0, v105
	v_rcp_f32_e32 v102, v102
	v_rcp_f32_e32 v103, v103
	v_rcp_f32_e32 v104, v104
	v_rcp_f32_e32 v105, v105
	v_pk_add_f32 v[106:107], v[12:13], v[116:117] op_sel:[0,1] op_sel_hi:[1,1]
	v_pk_add_f32 v[108:109], v[14:15], v[116:117] op_sel:[0,1] op_sel_hi:[1,1]
	v_pk_mul_f32 v[98:99], v[102:103], v[98:99]
	v_pk_mul_f32 v[100:101], v[104:105], v[100:101]
	v_pk_mul_f32 v[98:99], v[106:107], v[98:99]
	v_pk_mul_f32 v[100:101], v[108:109], v[100:101]
	s_nop 0
	v_cvt_pk_bf16_f32 v106, v98, v99
	v_cvt_pk_bf16_f32 v107, v100, v101
	global_store_dwordx2 v113, v[106:107], s[12:13] offset:128
	s_waitcnt vmcnt(2)
	v_lshlrev_b32_e32 v98, 16, v92
	v_and_b32_e32 v99, 0xffff0000, v92
	v_lshlrev_b32_e32 v100, 16, v93
	v_and_b32_e32 v101, 0xffff0000, v93
	v_mul_f32_e32 v102, 0x3d372713, v98
	v_mul_f32_e32 v103, 0x3d372713, v99
	v_mul_f32_e32 v104, 0x3d372713, v100
	v_mul_f32_e32 v105, 0x3d372713, v101
	v_mul_f32_e32 v102, v102, v98
	v_mul_f32_e32 v103, v103, v99
	v_mul_f32_e32 v104, v104, v100
	v_mul_f32_e32 v105, v105, v101
	v_fma_f32 v102, v102, v98, v98
	v_fma_f32 v103, v103, v99, v99
	v_fma_f32 v104, v104, v100, v100
	v_fma_f32 v105, v105, v101, v101
	v_mul_f32_e32 v102, 0x3f4c422a, v102
	v_mul_f32_e32 v103, 0x3f4c422a, v103
	v_mul_f32_e32 v104, 0x3f4c422a, v104
	v_mul_f32_e32 v105, 0x3f4c422a, v105
	v_mul_f32_e32 v102, -2.0, v102
	v_mul_f32_e32 v103, -2.0, v103
	v_mul_f32_e32 v104, -2.0, v104
	v_mul_f32_e32 v105, -2.0, v105
	v_mul_f32_e32 v102, 0x3fb8aa3b, v102
	v_mul_f32_e32 v103, 0x3fb8aa3b, v103
	v_mul_f32_e32 v104, 0x3fb8aa3b, v104
	v_mul_f32_e32 v105, 0x3fb8aa3b, v105
	v_exp_f32_e32 v102, v102
	v_exp_f32_e32 v103, v103
	v_exp_f32_e32 v104, v104
	v_exp_f32_e32 v105, v105
	v_add_f32_e32 v102, 1.0, v102
	v_add_f32_e32 v103, 1.0, v103
	v_add_f32_e32 v104, 1.0, v104
	v_add_f32_e32 v105, 1.0, v105
	v_rcp_f32_e32 v102, v102
	v_rcp_f32_e32 v103, v103
	v_rcp_f32_e32 v104, v104
	v_rcp_f32_e32 v105, v105
	v_pk_add_f32 v[106:107], v[8:9], v[116:117] op_sel:[0,1] op_sel_hi:[1,1]
	v_pk_add_f32 v[108:109], v[10:11], v[116:117] op_sel:[0,1] op_sel_hi:[1,1]
	v_pk_mul_f32 v[98:99], v[102:103], v[98:99]
	v_pk_mul_f32 v[100:101], v[104:105], v[100:101]
	v_pk_mul_f32 v[98:99], v[106:107], v[98:99]
	v_pk_mul_f32 v[100:101], v[108:109], v[100:101]
	s_nop 0
	v_cvt_pk_bf16_f32 v106, v98, v99
	v_cvt_pk_bf16_f32 v107, v100, v101
	global_store_dwordx2 v113, v[106:107], s[12:13] offset:160
	s_waitcnt vmcnt(1)
	v_lshlrev_b32_e32 v98, 16, v94
	v_and_b32_e32 v99, 0xffff0000, v94
	v_lshlrev_b32_e32 v100, 16, v95
	v_and_b32_e32 v101, 0xffff0000, v95
	v_mul_f32_e32 v102, 0x3d372713, v98
	v_mul_f32_e32 v103, 0x3d372713, v99
	v_mul_f32_e32 v104, 0x3d372713, v100
	v_mul_f32_e32 v105, 0x3d372713, v101
	v_mul_f32_e32 v102, v102, v98
	v_mul_f32_e32 v103, v103, v99
	v_mul_f32_e32 v104, v104, v100
	v_mul_f32_e32 v105, v105, v101
	v_fma_f32 v102, v102, v98, v98
	v_fma_f32 v103, v103, v99, v99
	v_fma_f32 v104, v104, v100, v100
	v_fma_f32 v105, v105, v101, v101
	v_mul_f32_e32 v102, 0x3f4c422a, v102
	v_mul_f32_e32 v103, 0x3f4c422a, v103
	v_mul_f32_e32 v104, 0x3f4c422a, v104
	v_mul_f32_e32 v105, 0x3f4c422a, v105
	v_mul_f32_e32 v102, -2.0, v102
	v_mul_f32_e32 v103, -2.0, v103
	v_mul_f32_e32 v104, -2.0, v104
	v_mul_f32_e32 v105, -2.0, v105
	v_mul_f32_e32 v102, 0x3fb8aa3b, v102
	v_mul_f32_e32 v103, 0x3fb8aa3b, v103
	v_mul_f32_e32 v104, 0x3fb8aa3b, v104
	v_mul_f32_e32 v105, 0x3fb8aa3b, v105
	v_exp_f32_e32 v102, v102
	v_exp_f32_e32 v103, v103
	v_exp_f32_e32 v104, v104
	v_exp_f32_e32 v105, v105
	v_add_f32_e32 v102, 1.0, v102
	v_add_f32_e32 v103, 1.0, v103
	v_add_f32_e32 v104, 1.0, v104
	v_add_f32_e32 v105, 1.0, v105
	v_rcp_f32_e32 v102, v102
	v_rcp_f32_e32 v103, v103
	v_rcp_f32_e32 v104, v104
	v_rcp_f32_e32 v105, v105
	v_pk_add_f32 v[106:107], v[4:5], v[116:117] op_sel:[0,1] op_sel_hi:[1,1]
	v_pk_add_f32 v[108:109], v[6:7], v[116:117] op_sel:[0,1] op_sel_hi:[1,1]
	v_pk_mul_f32 v[98:99], v[102:103], v[98:99]
	v_pk_mul_f32 v[100:101], v[104:105], v[100:101]
	v_pk_mul_f32 v[98:99], v[106:107], v[98:99]
	v_pk_mul_f32 v[100:101], v[108:109], v[100:101]
	s_nop 0
	v_cvt_pk_bf16_f32 v106, v98, v99
	v_cvt_pk_bf16_f32 v107, v100, v101
	global_store_dwordx2 v113, v[106:107], s[12:13] offset:192
	s_waitcnt vmcnt(0)
	v_lshlrev_b32_e32 v98, 16, v96
	v_and_b32_e32 v99, 0xffff0000, v96
	v_lshlrev_b32_e32 v100, 16, v97
	v_and_b32_e32 v101, 0xffff0000, v97
	v_mul_f32_e32 v102, 0x3d372713, v98
	v_mul_f32_e32 v103, 0x3d372713, v99
	v_mul_f32_e32 v104, 0x3d372713, v100
	v_mul_f32_e32 v105, 0x3d372713, v101
	v_mul_f32_e32 v102, v102, v98
	v_mul_f32_e32 v103, v103, v99
	v_mul_f32_e32 v104, v104, v100
	v_mul_f32_e32 v105, v105, v101
	v_fma_f32 v102, v102, v98, v98
	v_fma_f32 v103, v103, v99, v99
	v_fma_f32 v104, v104, v100, v100
	v_fma_f32 v105, v105, v101, v101
	v_mul_f32_e32 v102, 0x3f4c422a, v102
	v_mul_f32_e32 v103, 0x3f4c422a, v103
	v_mul_f32_e32 v104, 0x3f4c422a, v104
	v_mul_f32_e32 v105, 0x3f4c422a, v105
	v_mul_f32_e32 v102, -2.0, v102
	v_mul_f32_e32 v103, -2.0, v103
	v_mul_f32_e32 v104, -2.0, v104
	v_mul_f32_e32 v105, -2.0, v105
	v_mul_f32_e32 v102, 0x3fb8aa3b, v102
	v_mul_f32_e32 v103, 0x3fb8aa3b, v103
	v_mul_f32_e32 v104, 0x3fb8aa3b, v104
	v_mul_f32_e32 v105, 0x3fb8aa3b, v105
	v_exp_f32_e32 v102, v102
	v_exp_f32_e32 v103, v103
	v_exp_f32_e32 v104, v104
	v_exp_f32_e32 v105, v105
	v_add_f32_e32 v102, 1.0, v102
	v_add_f32_e32 v103, 1.0, v103
	v_add_f32_e32 v104, 1.0, v104
	v_add_f32_e32 v105, 1.0, v105
	v_rcp_f32_e32 v102, v102
	v_rcp_f32_e32 v103, v103
	v_rcp_f32_e32 v104, v104
	v_rcp_f32_e32 v105, v105
	v_pk_add_f32 v[106:107], v[0:1], v[116:117] op_sel:[0,1] op_sel_hi:[1,1]
	v_pk_add_f32 v[108:109], v[2:3], v[116:117] op_sel:[0,1] op_sel_hi:[1,1]
	v_pk_mul_f32 v[98:99], v[102:103], v[98:99]
	v_pk_mul_f32 v[100:101], v[104:105], v[100:101]
	v_pk_mul_f32 v[98:99], v[106:107], v[98:99]
	v_pk_mul_f32 v[100:101], v[108:109], v[100:101]
	s_nop 0
	v_cvt_pk_bf16_f32 v106, v98, v99
	v_cvt_pk_bf16_f32 v107, v100, v101
	global_store_dwordx2 v113, v[106:107], s[12:13] offset:224
	s_mov_b64 s[30:31], 0
